# phase-0 f32-to-bf16 cast loops unrolled x4 (8 loads in flight per wave) on top of attention softmax+PV reschedule and per-tile pacing
# baseline (speedup 1.0000x reference)
; DI u32x4 pk8(const f32x4& a, const f32x4& b) { u32x4 w; w.x = pk2(a[0], a[1]); w.y = pk2(a[2], a[3]); w.z = pk2(b[0], b[1]); w.w = pk2(b[2], b[3]); return w; }
; DI void cast_bf16(const float* src, bf16_t* dst, size_t n, size_t gt, size_t NGT) {
;     for (size_t i = gt; i < n / 8; i += NGT) { const f32x4 a = *(const f32x4*)(src + 8 * i), b = *(const f32x4*)(src + 8 * i + 4); *(u32x4*)(dst + 8 * i) = pk8(a, b); }
; }
; __global__ void __launch_bounds__(512, 2) mk_fwd(Args args) {
;     ...
;         cast_bf16(x_in, XB, (size_t)MTOK * 1024, gt, NGT);
.LBB0_1121:
	s_mov_b64 s[0:1], 0x800000
	v_cmp_gt_u64_e32 vcc, s[0:1], v[2:3]
	s_lshl_b64 s[0:1], s[68:69], 9
	v_lshlrev_b32_e32 v6, 5, v192
	v_lshlrev_b32_e32 v4, 4, v192
	s_and_saveexec_b64 s[4:5], vcc
	s_cbranch_execz .LBB0_1124
	s_lshl_b64 s[6:7], s[2:3], 14
	s_add_u32 s6, s12, s6
	v_mov_b32_e32 v7, 0
	s_addc_u32 s7, s13, s7
	v_lshl_add_u64 v[8:9], s[6:7], 0, v[6:7]
	s_lshl_b64 s[6:7], s[68:69], 14
	s_lshl_b64 s[8:9], s[2:3], 13
	s_add_u32 s8, s56, s8
	v_mov_b32_e32 v5, v7
	s_addc_u32 s9, s57, s9
	v_lshl_add_u64 v[10:11], s[8:9], 0, v[4:5]
	s_mov_b64 s[8:9], 0x8000000
	v_lshl_add_u64 v[8:9], v[8:9], 0, 16
	v_lshl_add_u64 v[10:11], v[10:11], 0, s[8:9]
	s_lshl_b64 s[8:9], s[68:69], 13
	s_mov_b64 s[10:11], 0
	s_mov_b64 s[12:13], 0x7fffff
	v_mov_b64_e32 v[12:13], v[2:3]
	s_lshl_b64 s[98:99], s[0:1], 2
	s_lshl_b64 s[100:101], s[0:1], 1
	s_add_u32 s100, s100, s0
	s_addc_u32 s101, s101, s1
	s_sub_u32 s100, 0x800000, s100
	s_subb_u32 s101, 0, s101
.Lcx_x_main:
	v_cmp_gt_i64_e32 vcc, s[100:101], v[12:13]
	s_nop 1
	s_xor_b64 vcc, vcc, exec
	s_cmp_lg_u64 vcc, 0
	s_cbranch_scc1 .Lcx_x_rem
	global_load_dwordx4 v[24:27], v[8:9], off offset:-16
	global_load_dwordx4 v[28:31], v[8:9], off
	v_lshl_add_u64 v[14:15], v[8:9], 0, s[6:7]
	global_load_dwordx4 v[32:35], v[14:15], off offset:-16
	global_load_dwordx4 v[36:39], v[14:15], off
	v_lshl_add_u64 v[14:15], v[14:15], 0, s[6:7]
	global_load_dwordx4 v[40:43], v[14:15], off offset:-16
	global_load_dwordx4 v[44:47], v[14:15], off
	v_lshl_add_u64 v[14:15], v[14:15], 0, s[6:7]
	global_load_dwordx4 v[48:51], v[14:15], off offset:-16
	global_load_dwordx4 v[52:55], v[14:15], off
	v_lshl_add_u64 v[8:9], v[14:15], 0, s[6:7]
	v_lshl_add_u64 v[12:13], v[12:13], 0, s[98:99]
	v_lshl_add_u64 v[16:17], v[10:11], 0, s[8:9]
	v_lshl_add_u64 v[18:19], v[16:17], 0, s[8:9]
	v_lshl_add_u64 v[20:21], v[18:19], 0, s[8:9]
	s_waitcnt vmcnt(6)
	v_cvt_pk_bf16_f32 v24, v24, v25
	v_cvt_pk_bf16_f32 v25, v26, v27
	v_cvt_pk_bf16_f32 v26, v28, v29
	v_cvt_pk_bf16_f32 v27, v30, v31
	global_store_dwordx4 v[10:11], v[24:27], off
	s_waitcnt vmcnt(5)
	v_cvt_pk_bf16_f32 v32, v32, v33
	v_cvt_pk_bf16_f32 v33, v34, v35
	v_cvt_pk_bf16_f32 v34, v36, v37
	v_cvt_pk_bf16_f32 v35, v38, v39
	global_store_dwordx4 v[16:17], v[32:35], off
	s_waitcnt vmcnt(4)
	v_cvt_pk_bf16_f32 v40, v40, v41
	v_cvt_pk_bf16_f32 v41, v42, v43
	v_cvt_pk_bf16_f32 v42, v44, v45
	v_cvt_pk_bf16_f32 v43, v46, v47
	global_store_dwordx4 v[18:19], v[40:43], off
	s_waitcnt vmcnt(3)
	v_cvt_pk_bf16_f32 v48, v48, v49
	v_cvt_pk_bf16_f32 v49, v50, v51
	v_cvt_pk_bf16_f32 v50, v52, v53
	v_cvt_pk_bf16_f32 v51, v54, v55
	global_store_dwordx4 v[20:21], v[48:51], off
	v_lshl_add_u64 v[10:11], v[20:21], 0, s[8:9]
	s_branch .Lcx_x_main
.Lcx_x_rem:
	v_cmp_ge_u64_e32 vcc, s[12:13], v[12:13]
	s_nop 1
	s_and_b64 vcc, vcc, exec
	s_cbranch_scc0 .LBB0_1124
	s_mov_b64 exec, vcc

; DI u32x4 pk8(const f32x4& a, const f32x4& b) { u32x4 w; w.x = pk2(a[0], a[1]); w.y = pk2(a[2], a[3]); w.z = pk2(b[0], b[1]); w.w = pk2(b[2], b[3]); return w; }
; DI void cast_bf16(const float* src, bf16_t* dst, size_t n, size_t gt, size_t NGT) {
;     for (size_t i = gt; i < n / 8; i += NGT) { const f32x4 a = *(const f32x4*)(src + 8 * i), b = *(const f32x4*)(src + 8 * i + 4); *(u32x4*)(dst + 8 * i) = pk8(a, b); }
; }
; __global__ void __launch_bounds__(512, 2) mk_fwd(Args args) {
;     ...
;         cast_bf16(p_in, PB, (size_t)2 * MTOK * 256, gt, NGT);
.LBB0_1124:
	s_or_b64 exec, exec, s[4:5]
	v_readlane_b32 s74, v255, 5
	s_mov_b64 s[4:5], 0x400000
	v_readlane_b32 s75, v255, 6
	v_cmp_gt_u64_e32 vcc, s[4:5], v[2:3]
	s_and_saveexec_b64 s[4:5], vcc
	s_cbranch_execz .LBB0_1127
	s_lshl_b64 s[6:7], s[2:3], 14
	s_add_u32 s6, s14, s6
	v_mov_b32_e32 v7, 0
	s_addc_u32 s7, s15, s7
	v_lshl_add_u64 v[8:9], s[6:7], 0, v[6:7]
	s_lshl_b64 s[6:7], s[68:69], 14
	s_lshl_b64 s[8:9], s[2:3], 13
	s_add_u32 s8, s56, s8
	v_mov_b32_e32 v5, v7
	s_addc_u32 s9, s57, s9
	v_lshl_add_u64 v[4:5], s[8:9], 0, v[4:5]
	s_mov_b64 s[8:9], 0x4000000
	v_lshl_add_u64 v[8:9], v[8:9], 0, 16
	v_lshl_add_u64 v[4:5], v[4:5], 0, s[8:9]
	s_lshl_b64 s[8:9], s[68:69], 13
	s_mov_b64 s[10:11], 0
	s_mov_b64 s[12:13], 0x3fffff
	v_mov_b64_e32 v[6:7], v[2:3]
	s_lshl_b64 s[98:99], s[0:1], 2
	s_lshl_b64 s[100:101], s[0:1], 1
	s_add_u32 s100, s100, s0
	s_addc_u32 s101, s101, s1
	s_sub_u32 s100, 0x400000, s100
	s_subb_u32 s101, 0, s101
.Lcx_p_main:
	v_cmp_gt_i64_e32 vcc, s[100:101], v[6:7]
	s_nop 1
	s_xor_b64 vcc, vcc, exec
	s_cmp_lg_u64 vcc, 0
	s_cbranch_scc1 .Lcx_p_rem
	global_load_dwordx4 v[24:27], v[8:9], off offset:-16
	global_load_dwordx4 v[28:31], v[8:9], off
	v_lshl_add_u64 v[14:15], v[8:9], 0, s[6:7]
	global_load_dwordx4 v[32:35], v[14:15], off offset:-16
	global_load_dwordx4 v[36:39], v[14:15], off
	v_lshl_add_u64 v[14:15], v[14:15], 0, s[6:7]
	global_load_dwordx4 v[40:43], v[14:15], off offset:-16
	global_load_dwordx4 v[44:47], v[14:15], off
	v_lshl_add_u64 v[14:15], v[14:15], 0, s[6:7]
	global_load_dwordx4 v[48:51], v[14:15], off offset:-16
	global_load_dwordx4 v[52:55], v[14:15], off
	v_lshl_add_u64 v[8:9], v[14:15], 0, s[6:7]
	v_lshl_add_u64 v[6:7], v[6:7], 0, s[98:99]
	v_lshl_add_u64 v[16:17], v[4:5], 0, s[8:9]
	v_lshl_add_u64 v[18:19], v[16:17], 0, s[8:9]
	v_lshl_add_u64 v[20:21], v[18:19], 0, s[8:9]
	s_waitcnt vmcnt(6)
	v_cvt_pk_bf16_f32 v24, v24, v25
	v_cvt_pk_bf16_f32 v25, v26, v27
	v_cvt_pk_bf16_f32 v26, v28, v29
	v_cvt_pk_bf16_f32 v27, v30, v31
	global_store_dwordx4 v[4:5], v[24:27], off
	s_waitcnt vmcnt(5)
	v_cvt_pk_bf16_f32 v32, v32, v33
	v_cvt_pk_bf16_f32 v33, v34, v35
	v_cvt_pk_bf16_f32 v34, v36, v37
	v_cvt_pk_bf16_f32 v35, v38, v39
	global_store_dwordx4 v[16:17], v[32:35], off
	s_waitcnt vmcnt(4)
	v_cvt_pk_bf16_f32 v40, v40, v41
	v_cvt_pk_bf16_f32 v41, v42, v43
	v_cvt_pk_bf16_f32 v42, v44, v45
	v_cvt_pk_bf16_f32 v43, v46, v47
	global_store_dwordx4 v[18:19], v[40:43], off
	s_waitcnt vmcnt(3)
	v_cvt_pk_bf16_f32 v48, v48, v49
	v_cvt_pk_bf16_f32 v49, v50, v51
	v_cvt_pk_bf16_f32 v50, v52, v53
	v_cvt_pk_bf16_f32 v51, v54, v55
	global_store_dwordx4 v[20:21], v[48:51], off
	v_lshl_add_u64 v[4:5], v[20:21], 0, s[8:9]
	s_branch .Lcx_p_main
.Lcx_p_rem:
	v_cmp_ge_u64_e32 vcc, s[12:13], v[6:7]
	s_nop 1
	s_and_b64 vcc, vcc, exec
	s_cbranch_scc0 .LBB0_1127
	s_mov_b64 exec, vcc
